# static priority raise (asm guide 6.3/7.4): s_setprio 2 for the gdn_prep triangular-solve waves 0-3 during S4, reset at item loop continue
# speedup vs baseline: 1.0097x; 1.0097x over previous
.LBB0_570:
	s_setprio 0
	s_or_b64 exec, exec, s[22:23]
	s_cmpk_lt_i32 s2, 0x1040
	s_cbranch_scc0 .LBB0_945

.LBB0_802:
	s_andn2_saveexec_b64 s[22:23], s[72:73]
	s_cbranch_execz .LBB0_570
	s_setprio 2
	s_add_i32 s0, s3, 0x8800
	v_mov_b32_e32 v0, s81
	v_mov_b32_e32 v2, s0
	v_cndmask_b32_e64 v2, v0, v2, s[18:19]
	v_lshlrev_b32_e32 v0, 2, v1
	v_add_u32_e32 v3, 0, v0
	v_lshl_add_u32 v18, v171, 1, v2
	v_add_u32_e32 v16, 0x1d900, v3
	ds_read_u16 v2, v18
	ds_read_b32 v3, v16
	v_add_u32_e32 v15, s97, v0
	s_waitcnt lgkmcnt(1)
	v_lshlrev_b32_e32 v2, 16, v2
	s_waitcnt lgkmcnt(0)
	v_mul_f32_e32 v2, v3, v2
	s_and_saveexec_b64 s[0:1], s[16:17]
	s_cbranch_execz .LBB0_805
	ds_read_b32 v3, v15
	s_waitcnt lgkmcnt(0)
	v_mul_f32_e32 v2, v2, v3
